# seam spin loops: s_sleep 0 instead of s_sleep 1 between polls (27 sites)
# speedup vs baseline: 1.0020x; 1.0011x over previous
; #define KARG ((const __attribute__((address_space(4))) Args*)__builtin_amdgcn_kernarg_segment_ptr())
; __device__ __forceinline__ unsigned xb_ld(unsigned* p)              { return __hip_atomic_load(p, __ATOMIC_RELAXED, __HIP_MEMORY_SCOPE_AGENT); }
; __device__ __forceinline__ void xcd_barrier_complete(unsigned* bar, unsigned x, unsigned& nloc, unsigned& nx) {
;     const unsigned G = (unsigned)KARG->grid;
;     unsigned sum, cnt, mine, sp = 0u;
;     for (;;) {
;         sum = 0u; cnt = 0u; mine = 0u;
; #pragma unroll
;         for (unsigned j = 0; j < 16; ++j) { const unsigned c = xb_ld(&bar[XB_XCNT(j)]); sum += c; cnt += (c > 0u) ? 1u : 0u; mine = (j == x) ? c : mine; }
;         if (sum == G) break;
;         __builtin_amdgcn_s_sleep(1);
;         if ((++sp & 255u) == 0u) { if (xb_ld(&bar[XB_TMO])) break; if (sp > XB_SPIN_CAP) { atomicAdd(&bar[XB_TMO], 1u); break; } }
;     }
.LBB0_25:
	global_load_dword v16, v17, s[10:11] sc1
	s_waitcnt lgkmcnt(0)
	global_load_dword v1, v17, s[12:13] sc1
	global_load_dword v2, v17, s[14:15] sc1
	global_load_dword v3, v17, s[16:17] sc1
	global_load_dword v4, v17, s[18:19] sc1
	global_load_dword v5, v17, s[20:21] sc1
	global_load_dword v6, v17, s[22:23] sc1
	global_load_dword v7, v17, s[24:25] sc1
	global_load_dword v8, v17, s[26:27] sc1
	global_load_dword v9, v17, s[28:29] sc1
	global_load_dword v10, v17, s[30:31] sc1
	global_load_dword v11, v17, s[34:35] sc1
	global_load_dword v12, v17, s[36:37] sc1
	global_load_dword v13, v17, s[38:39] sc1
	global_load_dword v14, v17, s[40:41] sc1
	global_load_dword v15, v17, s[42:43] sc1
	s_mov_b64 s[44:45], -1
	s_mov_b64 s[46:47], -1
	s_waitcnt vmcnt(14)
	v_add_u32_e32 v18, v1, v16
	s_waitcnt vmcnt(13)
	v_add_u32_e32 v18, v18, v2
	s_waitcnt vmcnt(12)
	v_add_u32_e32 v18, v18, v3
	s_waitcnt vmcnt(11)
	v_add_u32_e32 v18, v18, v4
	s_waitcnt vmcnt(10)
	v_add_u32_e32 v18, v18, v5
	s_waitcnt vmcnt(9)
	v_add_u32_e32 v18, v18, v6
	s_waitcnt vmcnt(8)
	v_add_u32_e32 v18, v18, v7
	s_waitcnt vmcnt(7)
	v_add_u32_e32 v18, v18, v8
	s_waitcnt vmcnt(6)
	v_add_u32_e32 v18, v18, v9
	s_waitcnt vmcnt(5)
	v_add_u32_e32 v18, v18, v10
	s_waitcnt vmcnt(4)
	v_add_u32_e32 v18, v18, v11
	s_waitcnt vmcnt(3)
	v_add_u32_e32 v18, v18, v12
	s_waitcnt vmcnt(2)
	v_add_u32_e32 v18, v18, v13
	s_waitcnt vmcnt(1)
	v_add_u32_e32 v18, v18, v14
	s_waitcnt vmcnt(0)
	v_add_u32_e32 v18, v18, v15
	v_cmp_eq_u32_e32 vcc, s3, v18
	s_cbranch_vccnz .LBB0_24
	s_and_b32 s44, s52, 0xff
	s_cmp_eq_u32 s44, 0
	s_mov_b64 s[44:45], -1
	s_mov_b64 s[56:57], -1
	s_sleep 0
	s_cbranch_scc1 .LBB0_29
	s_and_b64 vcc, exec, s[56:57]
	s_cbranch_vccz .LBB0_24

.LBB0_43:
	s_and_b32 s24, s28, 0xff
	s_mov_b64 s[22:23], -1
	s_cmp_lg_u32 s24, 0
	s_mov_b64 s[26:27], -1
	s_sleep 0
	s_cbranch_scc0 .LBB0_46
	s_and_b64 vcc, exec, s[26:27]
	s_cbranch_vccz .LBB0_42

.LBB0_60:
	s_and_b32 s22, s28, 0xff
	s_cmp_lg_u32 s22, 0
	s_mov_b64 s[24:25], -1
	s_sleep 0
	s_cbranch_scc0 .LBB0_63
	s_mov_b64 s[26:27], -1
	s_and_b64 vcc, exec, s[24:25]
	s_cbranch_vccz .LBB0_59

; #define KARG ((const __attribute__((address_space(4))) Args*)__builtin_amdgcn_kernarg_segment_ptr())
; __device__ __forceinline__ unsigned xb_ld(unsigned* p)              { return __hip_atomic_load(p, __ATOMIC_RELAXED, __HIP_MEMORY_SCOPE_AGENT); }
; __device__ __forceinline__ void xcd_barrier_complete(unsigned* bar, unsigned x, unsigned& nloc, unsigned& nx) {
;     const unsigned G = (unsigned)KARG->grid;
;     unsigned sum, cnt, mine, sp = 0u;
;     for (;;) {
;         sum = 0u; cnt = 0u; mine = 0u;
; #pragma unroll
;         for (unsigned j = 0; j < 16; ++j) { const unsigned c = xb_ld(&bar[XB_XCNT(j)]); sum += c; cnt += (c > 0u) ? 1u : 0u; mine = (j == x) ? c : mine; }
;         if (sum == G) break;
;         __builtin_amdgcn_s_sleep(1);
;         if ((++sp & 255u) == 0u) { if (xb_ld(&bar[XB_TMO])) break; if (sp > XB_SPIN_CAP) { atomicAdd(&bar[XB_TMO], 1u); break; } }
;     }
.LBB0_444:
	global_load_dword v16, v17, s[8:9] sc1
	s_waitcnt lgkmcnt(0)
	global_load_dword v1, v17, s[10:11] sc1
	global_load_dword v2, v17, s[12:13] sc1
	global_load_dword v3, v17, s[14:15] sc1
	global_load_dword v4, v17, s[16:17] sc1
	global_load_dword v5, v17, s[18:19] sc1
	global_load_dword v6, v17, s[20:21] sc1
	global_load_dword v7, v17, s[22:23] sc1
	global_load_dword v8, v17, s[24:25] sc1
	global_load_dword v9, v17, s[26:27] sc1
	global_load_dword v10, v17, s[28:29] sc1
	global_load_dword v11, v17, s[30:31] sc1
	global_load_dword v12, v17, s[34:35] sc1
	global_load_dword v13, v17, s[36:37] sc1
	global_load_dword v14, v17, s[38:39] sc1
	global_load_dword v15, v17, s[40:41] sc1
	s_mov_b64 s[42:43], -1
	s_mov_b64 s[44:45], -1
	s_waitcnt vmcnt(14)
	v_add_u32_e32 v18, v1, v16
	s_waitcnt vmcnt(13)
	v_add_u32_e32 v18, v18, v2
	s_waitcnt vmcnt(12)
	v_add_u32_e32 v18, v18, v3
	s_waitcnt vmcnt(11)
	v_add_u32_e32 v18, v18, v4
	s_waitcnt vmcnt(10)
	v_add_u32_e32 v18, v18, v5
	s_waitcnt vmcnt(9)
	v_add_u32_e32 v18, v18, v6
	s_waitcnt vmcnt(8)
	v_add_u32_e32 v18, v18, v7
	s_waitcnt vmcnt(7)
	v_add_u32_e32 v18, v18, v8
	s_waitcnt vmcnt(6)
	v_add_u32_e32 v18, v18, v9
	s_waitcnt vmcnt(5)
	v_add_u32_e32 v18, v18, v10
	s_waitcnt vmcnt(4)
	v_add_u32_e32 v18, v18, v11
	s_waitcnt vmcnt(3)
	v_add_u32_e32 v18, v18, v12
	s_waitcnt vmcnt(2)
	v_add_u32_e32 v18, v18, v13
	s_waitcnt vmcnt(1)
	v_add_u32_e32 v18, v18, v14
	s_waitcnt vmcnt(0)
	v_add_u32_e32 v18, v18, v15
	v_cmp_eq_u32_e32 vcc, s3, v18
	s_cbranch_vccnz .LBB0_443
	s_and_b32 s42, s52, 0xff
	s_cmp_eq_u32 s42, 0
	s_mov_b64 s[42:43], -1
	s_mov_b64 s[46:47], -1
	s_sleep 0
	s_cbranch_scc1 .LBB0_448
	s_and_b64 vcc, exec, s[46:47]
	s_cbranch_vccz .LBB0_443

.LBB0_462:
	s_and_b32 s22, s26, 0xff
	s_mov_b64 s[20:21], -1
	s_cmp_lg_u32 s22, 0
	s_mov_b64 s[24:25], -1
	s_sleep 0
	s_cbranch_scc0 .LBB0_465
	s_and_b64 vcc, exec, s[24:25]
	s_cbranch_vccz .LBB0_461

.LBB0_479:
	s_and_b32 s20, s26, 0xff
	s_cmp_lg_u32 s20, 0
	s_mov_b64 s[22:23], -1
	s_sleep 0
	s_cbranch_scc0 .LBB0_482
	s_mov_b64 s[24:25], -1
	s_and_b64 vcc, exec, s[22:23]
	s_cbranch_vccz .LBB0_478

; __device__ __forceinline__ unsigned xb_ld(unsigned* p)              { return __hip_atomic_load(p, __ATOMIC_RELAXED, __HIP_MEMORY_SCOPE_AGENT); }
; __device__ __forceinline__ void xcd_barrier_complete(unsigned* bar, unsigned x, unsigned& nloc, unsigned& nx) {
;     ...
;     for (;;) {
;         sum = 0u; cnt = 0u; mine = 0u;
; #pragma unroll
;         for (unsigned j = 0; j < 16; ++j) { const unsigned c = xb_ld(&bar[XB_XCNT(j)]); sum += c; cnt += (c > 0u) ? 1u : 0u; mine = (j == x) ? c : mine; }
;         if (sum == G) break;
;         __builtin_amdgcn_s_sleep(1);
;         if ((++sp & 255u) == 0u) { if (xb_ld(&bar[XB_TMO])) break; if (sp > XB_SPIN_CAP) { atomicAdd(&bar[XB_TMO], 1u); break; } }
;     }
.LBB0_1109:
	global_load_dword v15, v16, s[10:11] sc1
	s_waitcnt lgkmcnt(0)
	global_load_dword v0, v16, s[12:13] sc1
	global_load_dword v1, v16, s[14:15] sc1
	global_load_dword v2, v16, s[16:17] sc1
	global_load_dword v3, v16, s[18:19] sc1
	global_load_dword v4, v16, s[20:21] sc1
	global_load_dword v5, v16, s[22:23] sc1
	global_load_dword v6, v16, s[24:25] sc1
	global_load_dword v7, v16, s[26:27] sc1
	global_load_dword v8, v16, s[28:29] sc1
	global_load_dword v9, v16, s[30:31] sc1
	global_load_dword v10, v16, s[34:35] sc1
	global_load_dword v11, v16, s[36:37] sc1
	global_load_dword v12, v16, s[38:39] sc1
	global_load_dword v13, v16, s[40:41] sc1
	global_load_dword v14, v16, s[42:43] sc1
	s_mov_b64 s[44:45], -1
	s_mov_b64 s[46:47], -1
	s_waitcnt vmcnt(14)
	v_add_u32_e32 v17, v0, v15
	s_waitcnt vmcnt(13)
	v_add_u32_e32 v17, v17, v1
	s_waitcnt vmcnt(12)
	v_add_u32_e32 v17, v17, v2
	s_waitcnt vmcnt(11)
	v_add_u32_e32 v17, v17, v3
	s_waitcnt vmcnt(10)
	v_add_u32_e32 v17, v17, v4
	s_waitcnt vmcnt(9)
	v_add_u32_e32 v17, v17, v5
	s_waitcnt vmcnt(8)
	v_add_u32_e32 v17, v17, v6
	s_waitcnt vmcnt(7)
	v_add_u32_e32 v17, v17, v7
	s_waitcnt vmcnt(6)
	v_add_u32_e32 v17, v17, v8
	s_waitcnt vmcnt(5)
	v_add_u32_e32 v17, v17, v9
	s_waitcnt vmcnt(4)
	v_add_u32_e32 v17, v17, v10
	s_waitcnt vmcnt(3)
	v_add_u32_e32 v17, v17, v11
	s_waitcnt vmcnt(2)
	v_add_u32_e32 v17, v17, v12
	s_waitcnt vmcnt(1)
	v_add_u32_e32 v17, v17, v13
	s_waitcnt vmcnt(0)
	v_add_u32_e32 v17, v17, v14
	v_cmp_eq_u32_e32 vcc, s3, v17
	s_cbranch_vccnz .LBB0_1108
	s_and_b32 s44, s52, 0xff
	s_cmp_eq_u32 s44, 0
	s_mov_b64 s[44:45], -1
	s_mov_b64 s[48:49], -1
	s_sleep 0
	s_cbranch_scc1 .LBB0_1113
	s_and_b64 vcc, exec, s[48:49]
	s_cbranch_vccz .LBB0_1108
